# v33 + P14 gla_finalize: loop-invariant norm-weight loads hoisted out of the row loop (no per-row store-ack stalls)
# baseline (speedup 1.0000x reference)
; __device__ __forceinline__ void gla_finalize(const Ctx& F) {
;     const Params& P = *F.p;
;     const bf16_t* O = WSP(bf16_t, WS_RAW); const bf16_t* Y1 = WSP(bf16_t, WS_BIG + B_Y); bf16_t* CAT = WSP(bf16_t, WS_CAT);
;     const int gw = F.bid * 8 + F.wave, NGW = F.G * 8, lane = F.lane, d0 = (lane & 15) * 32;
;     for (int row = gw; row < SEQ; row += NGW) {
;         f32x4 o[8]; const u32x4* op0 = (const u32x4*)(O + ((size_t)(lane * 2) * SEQ + row) * 16); const u32x4* op1 = (const u32x4*)(O + ((size_t)(lane * 2 + 1) * SEQ + row) * 16); float ss = 0.f;
;         const u32x4 ob[4] = {op0[0], op0[1], op1[0], op1[1]};
; #pragma unroll
;         for (int i = 0; i < 8; ++i) { const u32x4 q4 = ob[i >> 1]; const unsigned w0 = (i & 1) ? q4.z : q4.x, w1 = (i & 1) ? q4.w : q4.y;
;             o[i] = (f32x4){__uint_as_float(w0 << 16), __uint_as_float(w0 & 0xffff0000u), __uint_as_float(w1 << 16), __uint_as_float(w1 & 0xffff0000u)}; ss += (o[i][0] * o[i][0] + o[i][1] * o[i][1]) + (o[i][2] * o[i][2] + o[i][3] * o[i][3]); }
;         ss += __shfl_xor(ss, 1); ss += __shfl_xor(ss, 2); ss += __shfl_xor(ss, 4); ss += __shfl_xor(ss, 8);
;         const float rstd = rsqrtf(ss * (1.0f / 512.0f) + EPS);
;         const u32x4* rp = (const u32x4*)(Y1 + (size_t)row * 6144 + 4096 + lane * 32); u32x4* cp = (u32x4*)(CAT + (size_t)row * 2048 + lane * 32);
.LBB0_1901:
	v_readlane_b32 s4, v247, 5
	v_readlane_b32 s5, v247, 6
	s_cmp_lt_i32 s4, 15
	s_cselect_b64 s[4:5], -1, 0
	s_and_b64 s[0:1], s[4:5], s[0:1]
	s_andn2_b64 vcc, exec, s[0:1]
	v_readlane_b32 s6, v247, 7
	v_readlane_b32 s7, v247, 8
	s_cbranch_vccnz .LBB0_1905
	s_lshl_b32 s0, s76, 3
	s_add_i32 s6, s0, s94
	s_cmpk_gt_i32 s6, 0x3fff
	s_cbranch_scc1 .LBB0_1905
	s_waitcnt vmcnt(0)
	v_mbcnt_lo_u32_b32 v2, -1, 0
	v_mbcnt_hi_u32_b32 v2, -1, v2
	v_and_b32_e32 v4, 64, v2
	s_waitcnt lgkmcnt(1)
	v_xor_b32_e32 v3, 1, v2
	v_add_u32_e32 v4, 64, v4
	v_cmp_lt_i32_e32 vcc, v3, v4
	s_waitcnt lgkmcnt(0)
	v_mov_b32_e32 v1, 0
	v_readlane_b32 s12, v247, 44
	v_cndmask_b32_e32 v3, v2, v3, vcc
	v_lshlrev_b32_e32 v38, 2, v3
	v_xor_b32_e32 v3, 2, v2
	v_cmp_lt_i32_e32 vcc, v3, v4
	v_readlane_b32 s20, v247, 52
	v_readlane_b32 s21, v247, 53
	v_cndmask_b32_e32 v3, v2, v3, vcc
	v_lshlrev_b32_e32 v39, 2, v3
	v_xor_b32_e32 v3, 4, v2
	v_cmp_lt_i32_e32 vcc, v3, v4
	s_ashr_i32 s7, s6, 31
	s_lshl_b64 s[0:1], s[6:7], 12
	v_cndmask_b32_e32 v3, v2, v3, vcc
	v_lshlrev_b32_e32 v40, 2, v3
	v_xor_b32_e32 v3, 8, v2
	v_cmp_lt_i32_e32 vcc, v3, v4
	s_lshl_b32 s8, s33, 3
	v_mov_b32_e32 v15, s1
	v_cndmask_b32_e32 v2, v2, v3, vcc
	v_lshlrev_b32_e32 v41, 2, v2
	v_lshlrev_b32_e32 v2, 7, v242
	v_and_b32_e32 v2, 0x780, v2
	v_mov_b32_e32 v3, v1
	v_lshl_add_u64 v[12:13], s[20:21], 0, v[2:3]
	v_lshlrev_b32_e32 v2, 6, v242
	v_or_b32_e32 v14, s0, v2
	s_mul_hi_i32 s0, s6, 0x3000
	s_mul_i32 s1, s6, 0x3000
	v_lshlrev_b32_e32 v0, 20, v242
	v_readlane_b32 s13, v247, 45
	v_readlane_b32 s14, v247, 46
	v_readlane_b32 s15, v247, 47
	v_readlane_b32 s16, v247, 48
	v_readlane_b32 s17, v247, 49
	v_readlane_b32 s18, v247, 50
	v_readlane_b32 s19, v247, 51
	v_readlane_b32 s22, v247, 54
	v_readlane_b32 s23, v247, 55
	s_ashr_i32 s9, s8, 31
	v_or_b32_e32 v16, s1, v2
	v_mov_b32_e32 v17, s0
	s_lshl_b64 s[0:1], s[6:7], 5
	s_lshl_b64 s[10:11], s[8:9], 12
	s_mul_i32 s12, s33, 0x18000
	s_mul_hi_i32 s13, s8, 0x3000
	v_lshl_add_u64 v[18:19], v[0:1], 0, s[0:1]
	s_lshl_b64 s[14:15], s[8:9], 5
	s_mov_b64 s[16:17], 0xac00000
	s_mov_b64 s[18:19], 0xac80000
	s_mov_b32 s3, 0xffff0000
	s_mov_b64 s[20:21], 0x16c02000
	s_mov_b32 s7, 0x16c02000
	v_mov_b32_e32 v42, 0x358637bd
	s_mov_b32 s9, 0x800000
	s_movk_i32 s22, 0x7fff
	s_mov_b32 s23, 0x12c00000
	v_readlane_b32 s24, v247, 56
	v_readlane_b32 s25, v247, 57
	v_readlane_b32 s26, v247, 58
	v_readlane_b32 s27, v247, 59
	global_load_dwordx4 v[160:163], v[12:13], off
	global_load_dwordx4 v[164:167], v[12:13], off offset:16
	global_load_dwordx4 v[168:171], v[12:13], off offset:32
	global_load_dwordx4 v[172:175], v[12:13], off offset:48
	global_load_dwordx4 v[176:179], v[12:13], off offset:64
	global_load_dwordx4 v[180:183], v[12:13], off offset:80
	global_load_dwordx4 v[184:187], v[12:13], off offset:96
	global_load_dwordx4 v[188:191], v[12:13], off offset:112
	s_waitcnt vmcnt(0)
.LBB0_1904:
	v_lshl_add_u64 v[20:21], s[92:93], 0, v[18:19]
	v_lshl_add_u64 v[8:9], s[92:93], 0, v[16:17]
	v_add_co_u32_e32 v54, vcc, 0xac00000, v20
	v_add_co_u32_e64 v58, s[0:1], s7, v8
	v_lshl_add_u64 v[10:11], s[92:93], 0, v[14:15]
	s_nop 0
	v_addc_co_u32_e64 v59, s[0:1], 0, v9, s[0:1]
	v_addc_co_u32_e32 v55, vcc, 0, v21, vcc
	v_lshl_add_u64 v[28:29], v[20:21], 0, s[16:17]
	v_lshl_add_u64 v[52:53], v[20:21], 0, s[18:19]
	v_add_co_u32_e64 v22, s[0:1], s23, v10
	v_add_co_u32_e32 v20, vcc, 0xac80000, v20
	v_mov_b32_e32 v0, v164
	v_mov_b32_e32 v1, v165
	v_mov_b32_e32 v2, v166
	v_mov_b32_e32 v3, v167
	v_mov_b32_e32 v4, v160
	v_mov_b32_e32 v5, v161
	v_mov_b32_e32 v6, v162
	v_mov_b32_e32 v7, v163
	v_lshl_add_u64 v[56:57], v[8:9], 0, s[20:21]
	v_addc_co_u32_e64 v23, s[0:1], 0, v11, s[0:1]
	global_load_dwordx4 v[24:27], v[28:29], off offset:16
	global_load_dwordx4 v[44:47], v[52:53], off offset:16
	global_load_dwordx4 v[30:33], v[58:59], off
	global_load_dwordx4 v[34:37], v[56:57], off offset:16
	global_load_dwordx4 v[48:51], v[56:57], off offset:32
	global_load_dwordx4 v[8:11], v[56:57], off offset:48
	v_addc_co_u32_e32 v21, vcc, 0, v21, vcc
	global_load_dwordx4 v[52:55], v[54:55], off
	s_add_i32 s6, s6, s8
	global_load_dwordx4 v[56:59], v[20:21], off
	v_lshl_add_u64 v[14:15], v[14:15], 0, s[10:11]
	v_lshl_add_u64 v[16:17], v[16:17], 0, s[12:13]
	v_lshl_add_u64 v[18:19], v[18:19], 0, s[14:15]
	s_cmpk_lt_i32 s6, 0x4000
	s_waitcnt vmcnt(9)
	v_mov_b32_e32 v62, v0
	s_waitcnt vmcnt(8)
	v_mov_b32_e32 v60, v4
	s_waitcnt vmcnt(7)
	v_and_b32_e32 v70, 0xffff0000, v26
	s_waitcnt vmcnt(6)
	v_lshlrev_b32_e32 v4, 16, v44
	v_and_b32_e32 v0, 0xffff0000, v44
	v_lshlrev_b32_e32 v28, 16, v45
	s_waitcnt vmcnt(5)
	v_and_b32_e32 v75, 0xffff0000, v31
	v_lshlrev_b32_e32 v76, 16, v32
	v_lshlrev_b32_e32 v20, 16, v46
	s_waitcnt vmcnt(1)
	v_lshlrev_b32_e32 v93, 16, v53
	v_lshlrev_b32_e32 v92, 16, v52
	v_and_b32_e32 v53, 0xffff0000, v53
	v_and_b32_e32 v52, 0xffff0000, v52
	v_lshlrev_b32_e32 v95, 16, v55
	v_lshlrev_b32_e32 v94, 16, v54
	v_and_b32_e32 v55, 0xffff0000, v55
	v_and_b32_e32 v54, 0xffff0000, v54
	v_lshlrev_b32_e32 v65, 16, v25
	v_lshlrev_b32_e32 v64, 16, v24
	v_and_b32_e32 v67, 0xffff0000, v25
	v_and_b32_e32 v66, 0xffff0000, v24
	v_lshlrev_b32_e32 v68, 16, v26
	v_lshlrev_b32_e32 v72, 16, v27
	v_and_b32_e32 v29, 0xffff0000, v45
	v_lshlrev_b32_e32 v81, 16, v35
	v_lshlrev_b32_e32 v80, 16, v34
	v_and_b32_e32 v83, 0xffff0000, v35
	v_and_b32_e32 v82, 0xffff0000, v34
	v_lshlrev_b32_e32 v85, 16, v37
	v_lshlrev_b32_e32 v84, 16, v36
	v_and_b32_e32 v87, 0xffff0000, v37
	v_and_b32_e32 v86, 0xffff0000, v36
	v_lshlrev_b32_e32 v35, 16, v51
	v_lshlrev_b32_e32 v34, 16, v50
	v_and_b32_e32 v37, 0xffff0000, v51
	v_and_b32_e32 v36, 0xffff0000, v50
	v_lshlrev_b32_e32 v21, 16, v47
	v_and_b32_e32 v25, 0xffff0000, v47
	v_and_b32_e32 v24, 0xffff0000, v46
	v_mul_f32_e32 v51, v70, v70
	v_mul_f32_e32 v89, v4, v4
	v_mul_f32_e32 v91, v0, v0
	v_mul_f32_e32 v50, v28, v28
	v_mul_f32_e32 v104, 0xbfb8aa3b, v75
	v_mul_f32_e32 v112, 0xbfb8aa3b, v76
	v_mov_b32_e32 v88, v20
	v_mov_b32_e32 v90, v20
	s_waitcnt vmcnt(0)
; __device__ __forceinline__ unsigned pk2(float lo, float hi) { return f2bf(lo) | (f2bf(hi) << 16); }
; __device__ __forceinline__ float siluf_(float x) { return x * __builtin_amdgcn_rcpf(1.0f + __expf(-x)); }
; __device__ __forceinline__ void gla_finalize(const Ctx& F) {
;     ...
;         for (int i = 0; i < 8; ++i) { const u32x4 q4 = ob[i >> 1]; const unsigned w0 = (i & 1) ? q4.z : q4.x, w1 = (i & 1) ? q4.w : q4.y;
;             o[i] = (f32x4){__uint_as_float(w0 << 16), __uint_as_float(w0 & 0xffff0000u), __uint_as_float(w1 << 16), __uint_as_float(w1 & 0xffff0000u)}; ss += (o[i][0] * o[i][0] + o[i][1] * o[i][1]) + (o[i][2] * o[i][2] + o[i][3] * o[i][3]); }
;         ss += __shfl_xor(ss, 1); ss += __shfl_xor(ss, 2); ss += __shfl_xor(ss, 4); ss += __shfl_xor(ss, 8);
;         const float rstd = rsqrtf(ss * (1.0f / 512.0f) + EPS);
;         const u32x4* rp = (const u32x4*)(Y1 + (size_t)row * 6144 + 4096 + lane * 32); u32x4* cp = (u32x4*)(CAT + (size_t)row * 2048 + lane * 32);
; #pragma unroll
;         for (int i = 0; i < 4; ++i) { const u32x4 rv = rp[i]; const unsigned rr[4] = {rv.x, rv.y, rv.z, rv.w}; unsigned ov[4];
; #pragma unroll
;             for (int j = 0; j < 4; ++j) { const int e = i * 8 + j * 2; const float r0 = __uint_as_float(rr[j] << 16), r1 = __uint_as_float(rr[j] & 0xffff0000u);
;                 const float x0 = o[e >> 2][e & 3], x1 = o[(e + 1) >> 2][(e + 1) & 3];
;                 ov[j] = pk2(x0 * rstd * P.in[36][d0 + e] * siluf_(r0), x1 * rstd * P.in[36][d0 + e + 1] * siluf_(r1)); }
	v_lshlrev_b32_e32 v101, 16, v59
	v_lshlrev_b32_e32 v100, 16, v58
	v_and_b32_e32 v59, 0xffff0000, v59
	v_and_b32_e32 v58, 0xffff0000, v58
	v_mov_b32_e32 v106, v52
	v_mov_b32_e32 v107, v54
	v_mov_b32_e32 v110, v53
	v_mov_b32_e32 v111, v55
	v_and_b32_e32 v73, 0xffff0000, v27
	v_lshlrev_b32_e32 v45, 16, v31
	v_lshlrev_b32_e32 v44, 16, v30
	v_and_b32_e32 v74, 0xffff0000, v30
	v_lshlrev_b32_e32 v77, 16, v33
	v_and_b32_e32 v79, 0xffff0000, v33
	v_and_b32_e32 v78, 0xffff0000, v32
	v_lshlrev_b32_e32 v31, 16, v49
	v_lshlrev_b32_e32 v30, 16, v48
	v_and_b32_e32 v33, 0xffff0000, v49
	v_and_b32_e32 v32, 0xffff0000, v48
	v_mul_f32_e32 v49, v68, v68
	v_mul_f32_e32 v48, v72, v72
	v_pk_mul_f32 v[96:97], v[24:25], v[24:25]
	v_pk_mul_f32 v[98:99], v[20:21], v[20:21]
	v_pk_fma_f32 v[102:103], v[28:29], v[28:29], v[50:51] op_sel_hi:[1,1,0]
	v_exp_f32_e32 v132, v104
	v_mov_b32_e32 v104, v92
	v_mov_b32_e32 v105, v94
	v_mov_b32_e32 v108, v93
	v_mov_b32_e32 v109, v95
	v_exp_f32_e32 v133, v112
	v_lshlrev_b32_e32 v112, 16, v56
	v_pk_add_f32 v[88:89], v[88:89], v[90:91]
	v_pk_mul_f32 v[90:91], v[58:59], v[58:59]
	v_pk_mul_f32 v[106:107], v[106:107], v[106:107]
	v_pk_mul_f32 v[110:111], v[110:111], v[110:111]
	v_mov_b32_e32 v69, v72
	v_mov_b32_e32 v71, v73
	v_pk_fma_f32 v[72:73], v[72:73], v[72:73], v[48:49] op_sel_hi:[1,1,0]
	v_mov_b32_e32 v48, v112
	v_mov_b32_e32 v50, v112
	v_mov_b32_e32 v88, v98
	v_mov_b32_e32 v102, v96
	v_pk_fma_f32 v[90:91], v[100:101], v[100:101], v[90:91]
	v_pk_fma_f32 v[104:105], v[104:105], v[104:105], v[106:107]
	v_pk_fma_f32 v[106:107], v[108:109], v[108:109], v[110:111]
	v_pk_mul_f32 v[46:47], v[66:67], v[66:67]
	v_mul_f32_e32 v113, 0xbfb8aa3b, v78
	v_pk_add_f32 v[48:49], v[48:49], v[50:51]
	v_pk_add_f32 v[50:51], v[88:89], v[102:103]
	v_pk_add_f32 v[88:89], v[90:91], v[90:91] op_sel_hi:[0,1]
	v_pk_add_f32 v[90:91], v[104:105], v[106:107]
	v_mul_f32_e32 v114, 0xbfb8aa3b, v77
	v_mul_f32_e32 v115, 0xbfb8aa3b, v79
	v_mul_f32_e32 v116, 0xbfb8aa3b, v80
	v_mul_f32_e32 v117, 0xbfb8aa3b, v82
	v_pk_fma_f32 v[46:47], v[64:65], v[64:65], v[46:47]
	v_exp_f32_e32 v134, v113
	v_lshlrev_b32_e32 v113, 16, v57
	v_and_b32_e32 v57, 0xffff0000, v57
	v_and_b32_e32 v56, 0xffff0000, v56
	v_pk_add_f32 v[90:91], v[90:91], v[90:91] op_sel_hi:[0,1]
	v_exp_f32_e32 v135, v114
	v_exp_f32_e32 v136, v115
	v_exp_f32_e32 v137, v116
	v_exp_f32_e32 v138, v117
	v_pk_add_f32 v[46:47], v[46:47], v[46:47] op_sel_hi:[0,1]
	v_pk_mul_f32 v[114:115], v[56:57], v[56:57]
	v_pk_mul_f32 v[116:117], v[112:113], v[112:113]
	v_add_f32_e32 v90, 1.0, v133
	v_mov_b32_e32 v72, v114
	v_mov_b32_e32 v46, v115
	v_mov_b32_e32 v48, v116
	v_rcp_f32_e32 v102, v90
	v_mov_b32_e32 v90, v117
	v_mov_b32_e32 v63, v2
	v_mov_b32_e32 v2, v1
	v_mul_f32_e32 v1, 0xbfb8aa3b, v44
	v_pk_add_f32 v[48:49], v[48:49], v[72:73]
	v_pk_add_f32 v[46:47], v[90:91], v[46:47]
	v_mov_b32_e32 v61, v6
	v_mov_b32_e32 v6, v5
	v_mul_f32_e32 v5, 0xbfb8aa3b, v74
	v_exp_f32_e32 v1, v1
	v_pk_add_f32 v[46:47], v[48:49], v[46:47]
	v_exp_f32_e32 v5, v5
	v_pk_add_f32 v[46:47], v[46:47], v[46:47] op_sel_hi:[0,1]
	v_mov_b32_e32 v88, v99
	v_mov_b32_e32 v46, v97
	v_pk_add_f32 v[46:47], v[88:89], v[46:47]
	v_add_f32_e32 v1, 1.0, v1
	v_pk_add_f32 v[46:47], v[50:51], v[46:47]
	v_add_f32_e32 v5, 1.0, v5
	v_rcp_f32_e32 v72, v1
	v_add_f32_e32 v1, v46, v47
	v_rcp_f32_e32 v98, v5
	ds_bpermute_b32 v5, v38, v1
	v_mul_f32_e32 v43, 0xbfb8aa3b, v45
	v_mul_f32_e32 v118, 0xbfb8aa3b, v81
	v_mul_f32_e32 v119, 0xbfb8aa3b, v83
	v_mul_f32_e32 v120, 0xbfb8aa3b, v84
	s_waitcnt lgkmcnt(0)
	v_add_f32_e32 v1, v1, v5
	ds_bpermute_b32 v5, v39, v1
	v_mul_f32_e32 v122, 0xbfb8aa3b, v85
	v_exp_f32_e32 v43, v43
	v_exp_f32_e32 v118, v118
	v_exp_f32_e32 v119, v119
	s_waitcnt lgkmcnt(0)
	v_add_f32_e32 v1, v1, v5
	ds_bpermute_b32 v5, v40, v1
	v_exp_f32_e32 v120, v120
	v_exp_f32_e32 v122, v122
	v_add_f32_e32 v43, 1.0, v43
	v_add_f32_e32 v103, 1.0, v134
	s_waitcnt lgkmcnt(0)
	v_add_f32_e32 v1, v1, v5
	ds_bpermute_b32 v5, v41, v1
	v_add_f32_e32 v105, 1.0, v135
	v_add_f32_e32 v106, 1.0, v136
	v_add_f32_e32 v107, 1.0, v137
	v_add_f32_e32 v109, 1.0, v118
	s_waitcnt lgkmcnt(0)
	v_add_f32_e32 v1, v1, v5
	v_fmamk_f32 v1, v1, 0x3b000000, v42
	v_mul_f32_e32 v5, 0x4b800000, v1
	v_cmp_gt_f32_e32 vcc, s9, v1
	v_add_f32_e32 v110, 1.0, v119
	v_add_f32_e32 v111, 1.0, v120
	v_cndmask_b32_e32 v1, v1, v5, vcc
	v_add_f32_e32 v115, 1.0, v122
	v_rsq_f32_e32 v1, v1
	v_rcp_f32_e32 v73, v43
	v_rcp_f32_e32 v104, v103
	v_rcp_f32_e32 v103, v105
	v_rcp_f32_e32 v105, v106
	v_rcp_f32_e32 v106, v107
	v_rcp_f32_e32 v107, v109
	v_rcp_f32_e32 v109, v110
	v_rcp_f32_e32 v110, v111
	v_rcp_f32_e32 v111, v115
	v_add_f32_e32 v96, 1.0, v132
	v_rcp_f32_e32 v99, v96
	v_mul_f32_e32 v5, 0x45800000, v1
	v_pk_mul_f32 v[44:45], v[72:73], v[44:45]
	v_pk_mul_f32 v[72:73], v[102:103], v[76:77]
	v_pk_mul_f32 v[76:77], v[106:107], v[80:81]
	v_pk_mul_f32 v[80:81], v[110:111], v[84:85]
	v_cndmask_b32_e32 v84, v1, v5, vcc
	v_pk_mul_f32 v[46:47], v[84:85], v[92:93] op_sel_hi:[0,1]
	v_pk_mul_f32 v[50:51], v[84:85], v[52:53] op_sel_hi:[0,1]
	v_pk_mul_f32 v[52:53], v[84:85], v[94:95] op_sel_hi:[0,1]
	v_pk_mul_f32 v[54:55], v[84:85], v[54:55] op_sel_hi:[0,1]
	v_pk_mul_f32 v[48:49], v[98:99], v[74:75]
	v_pk_mul_f32 v[74:75], v[104:105], v[78:79]
	v_pk_mul_f32 v[46:47], v[60:61], v[46:47]
	v_pk_mul_f32 v[6:7], v[6:7], v[50:51]
	v_pk_mul_f32 v[50:51], v[62:63], v[52:53]
	v_pk_mul_f32 v[2:3], v[2:3], v[54:55]
	v_pk_mul_f32 v[44:45], v[44:45], v[46:47]
	v_pk_mul_f32 v[6:7], v[48:49], v[6:7]
	v_pk_mul_f32 v[46:47], v[72:73], v[50:51]
	v_pk_mul_f32 v[2:3], v[74:75], v[2:3]
	v_bfe_u32 v43, v7, 16, 1
	v_bfe_u32 v1, v3, 16, 1
	v_bfe_u32 v5, v2, 16, 1
; __device__ __forceinline__ unsigned pk2(float lo, float hi) { return f2bf(lo) | (f2bf(hi) << 16); }
; __device__ __forceinline__ float siluf_(float x) { return x * __builtin_amdgcn_rcpf(1.0f + __expf(-x)); }
; __device__ __forceinline__ void gla_finalize(const Ctx& F) {
;     ...
;         for (int i = 0; i < 4; ++i) { const u32x4 rv = rp[i]; const unsigned rr[4] = {rv.x, rv.y, rv.z, rv.w}; unsigned ov[4];
; #pragma unroll
;             for (int j = 0; j < 4; ++j) { const int e = i * 8 + j * 2; const float r0 = __uint_as_float(rr[j] << 16), r1 = __uint_as_float(rr[j] & 0xffff0000u);
;                 const float x0 = o[e >> 2][e & 3], x1 = o[(e + 1) >> 2][(e + 1) & 3];
;                 ov[j] = pk2(x0 * rstd * P.in[36][d0 + e] * siluf_(r0), x1 * rstd * P.in[36][d0 + e + 1] * siluf_(r1)); }
;             cp[i] = (u32x4){ov[0], ov[1], ov[2], ov[3]}; }
	v_bfe_u32 v49, v44, 16, 1
	v_bfe_u32 v50, v45, 16, 1
	v_bfe_u32 v51, v46, 16, 1
	v_bfe_u32 v52, v47, 16, 1
	v_bfe_u32 v48, v6, 16, 1
	v_add3_u32 v7, v7, v43, s22
	v_add3_u32 v2, v2, v5, s22
	v_add3_u32 v1, v3, v1, s22
	v_add3_u32 v3, v47, v52, s22
	v_add3_u32 v5, v46, v51, s22
	v_add3_u32 v43, v45, v50, s22
	v_add3_u32 v44, v44, v49, s22
	v_add3_u32 v6, v6, v48, s22
	v_lshrrev_b32_e32 v44, 16, v44
	v_lshrrev_b32_e32 v43, 16, v43
	v_lshrrev_b32_e32 v5, 16, v5
	v_lshrrev_b32_e32 v3, 16, v3
	v_and_or_b32 v47, v1, s3, v3
	v_and_or_b32 v46, v2, s3, v5
	v_and_or_b32 v45, v7, s3, v43
	v_and_or_b32 v44, v6, s3, v44
	global_store_dwordx4 v[22:23], v[44:47], off
	s_nop 1
	v_mov_b32_e32 v44, v168
	v_mov_b32_e32 v45, v169
	v_mov_b32_e32 v46, v170
	v_mov_b32_e32 v47, v171
	s_nop 0
	v_mov_b32_e32 v48, v172
	v_mov_b32_e32 v49, v173
	v_mov_b32_e32 v50, v174
	v_mov_b32_e32 v51, v175
	v_mul_f32_e32 v121, 0xbfb8aa3b, v86
	v_mul_f32_e32 v123, 0xbfb8aa3b, v87
	v_exp_f32_e32 v121, v121
	v_exp_f32_e32 v123, v123
	v_add_f32_e32 v108, 1.0, v138
	v_rcp_f32_e32 v108, v108
	v_add_f32_e32 v114, 1.0, v121
	v_add_f32_e32 v116, 1.0, v123
	v_rcp_f32_e32 v114, v114
	v_rcp_f32_e32 v115, v116
	v_pk_mul_f32 v[64:65], v[84:85], v[64:65] op_sel_hi:[0,1]
	v_pk_mul_f32 v[68:69], v[84:85], v[68:69] op_sel_hi:[0,1]
	v_pk_mul_f32 v[66:67], v[84:85], v[66:67] op_sel_hi:[0,1]
	v_pk_mul_f32 v[70:71], v[84:85], v[70:71] op_sel_hi:[0,1]
	v_pk_mul_f32 v[78:79], v[108:109], v[82:83]
	v_pk_mul_f32 v[82:83], v[114:115], v[86:87]
	v_mul_f32_e32 v124, 0xbfb8aa3b, v30
	v_mul_f32_e32 v125, 0xbfb8aa3b, v32
	v_mul_f32_e32 v126, 0xbfb8aa3b, v31
	v_mul_f32_e32 v127, 0xbfb8aa3b, v33
	v_mul_f32_e32 v128, 0xbfb8aa3b, v34
	v_mul_f32_e32 v129, 0xbfb8aa3b, v36
	v_mul_f32_e32 v130, 0xbfb8aa3b, v35
	v_mul_f32_e32 v131, 0xbfb8aa3b, v37
	v_exp_f32_e32 v124, v124
	v_exp_f32_e32 v125, v125
	v_exp_f32_e32 v126, v126
	v_exp_f32_e32 v127, v127
	v_exp_f32_e32 v128, v128
	v_exp_f32_e32 v129, v129
	v_exp_f32_e32 v130, v130
	v_exp_f32_e32 v131, v131
	v_add_f32_e32 v118, 1.0, v124
	v_add_f32_e32 v119, 1.0, v125
	v_add_f32_e32 v120, 1.0, v126
	v_add_f32_e32 v121, 1.0, v127
	v_add_f32_e32 v122, 1.0, v128
	v_add_f32_e32 v123, 1.0, v129
	v_add_f32_e32 v124, 1.0, v130
	v_rcp_f32_e32 v54, v123
	v_rcp_f32_e32 v53, v124
	v_lshlrev_b32_e32 v27, 16, v9
	v_lshlrev_b32_e32 v26, 16, v8
	v_pk_mul_f32 v[20:21], v[84:85], v[20:21] op_sel_hi:[0,1]
	v_pk_mul_f32 v[24:25], v[84:85], v[24:25] op_sel_hi:[0,1]
	v_mov_b32_e32 v2, v44
	v_mov_b32_e32 v3, v46
	v_mov_b32_e32 v6, v48
	v_mov_b32_e32 v7, v50
	v_mov_b32_e32 v46, v45
	v_mov_b32_e32 v50, v49
	v_pk_mul_f32 v[2:3], v[2:3], v[64:65]
	v_pk_mul_f32 v[6:7], v[6:7], v[68:69]
	v_pk_mul_f32 v[44:45], v[46:47], v[66:67]
	v_pk_mul_f32 v[46:47], v[50:51], v[70:71]
	v_pk_mul_f32 v[2:3], v[76:77], v[2:3]
	v_pk_mul_f32 v[6:7], v[80:81], v[6:7]
	v_pk_mul_f32 v[44:45], v[78:79], v[44:45]
	v_pk_mul_f32 v[46:47], v[82:83], v[46:47]
	v_bfe_u32 v49, v2, 16, 1
	v_bfe_u32 v50, v3, 16, 1
	v_bfe_u32 v51, v6, 16, 1
	v_bfe_u32 v52, v7, 16, 1
	v_bfe_u32 v1, v47, 16, 1
	v_bfe_u32 v5, v46, 16, 1
	v_bfe_u32 v43, v45, 16, 1
	v_bfe_u32 v48, v44, 16, 1
	v_add3_u32 v7, v7, v52, s22
	v_add3_u32 v6, v6, v51, s22
	v_add3_u32 v3, v3, v50, s22
	v_add3_u32 v2, v2, v49, s22
	v_add3_u32 v44, v44, v48, s22
	v_add3_u32 v43, v45, v43, s22
	v_add3_u32 v5, v46, v5, s22
	v_add3_u32 v1, v47, v1, s22
	v_lshrrev_b32_e32 v2, 16, v2
	v_lshrrev_b32_e32 v3, 16, v3
	v_lshrrev_b32_e32 v6, 16, v6
	v_lshrrev_b32_e32 v7, 16, v7
	v_and_or_b32 v47, v1, s3, v7
	v_and_or_b32 v46, v5, s3, v6
	v_and_or_b32 v45, v43, s3, v3
	v_and_or_b32 v44, v44, s3, v2
	global_store_dwordx4 v[22:23], v[44:47], off offset:16
	s_nop 1
	v_mov_b32_e32 v44, v176
	v_mov_b32_e32 v45, v177
	v_mov_b32_e32 v46, v178
	v_mov_b32_e32 v47, v179
	s_nop 0
	v_mov_b32_e32 v48, v180
	v_mov_b32_e32 v49, v181
	v_mov_b32_e32 v50, v182
	v_mov_b32_e32 v51, v183
	v_add_f32_e32 v1, 1.0, v131
	v_rcp_f32_e32 v2, v118
	v_rcp_f32_e32 v6, v119
	v_rcp_f32_e32 v3, v120
	v_rcp_f32_e32 v7, v121
	v_rcp_f32_e32 v52, v122
	v_rcp_f32_e32 v55, v1
	v_pk_mul_f32 v[2:3], v[2:3], v[30:31]
	v_pk_mul_f32 v[6:7], v[6:7], v[32:33]
	v_pk_mul_f32 v[30:31], v[52:53], v[34:35]
	v_pk_mul_f32 v[32:33], v[54:55], v[36:37]
	v_pk_mul_f32 v[34:35], v[84:85], v[112:113] op_sel_hi:[0,1]
; __device__ __forceinline__ unsigned pk2(float lo, float hi) { return f2bf(lo) | (f2bf(hi) << 16); }
; __device__ __forceinline__ float siluf_(float x) { return x * __builtin_amdgcn_rcpf(1.0f + __expf(-x)); }
; __device__ __forceinline__ void gla_finalize(const Ctx& F) {
;     ...
;         for (int i = 0; i < 4; ++i) { const u32x4 rv = rp[i]; const unsigned rr[4] = {rv.x, rv.y, rv.z, rv.w}; unsigned ov[4];
; #pragma unroll
;             for (int j = 0; j < 4; ++j) { const int e = i * 8 + j * 2; const float r0 = __uint_as_float(rr[j] << 16), r1 = __uint_as_float(rr[j] & 0xffff0000u);
;                 const float x0 = o[e >> 2][e & 3], x1 = o[(e + 1) >> 2][(e + 1) & 3];
;                 ov[j] = pk2(x0 * rstd * P.in[36][d0 + e] * siluf_(r0), x1 * rstd * P.in[36][d0 + e + 1] * siluf_(r1)); }
;             cp[i] = (u32x4){ov[0], ov[1], ov[2], ov[3]}; }
;     }
	v_pk_mul_f32 v[36:37], v[84:85], v[56:57] op_sel_hi:[0,1]
	v_pk_mul_f32 v[52:53], v[84:85], v[100:101] op_sel_hi:[0,1]
	v_pk_mul_f32 v[54:55], v[84:85], v[58:59] op_sel_hi:[0,1]
	v_mov_b32_e32 v56, v44
	v_mov_b32_e32 v57, v46
	v_mov_b32_e32 v46, v45
	v_mov_b32_e32 v44, v48
	v_mov_b32_e32 v45, v50
	v_mov_b32_e32 v50, v49
	v_pk_mul_f32 v[34:35], v[34:35], v[56:57]
	v_pk_mul_f32 v[44:45], v[52:53], v[44:45]
	v_pk_mul_f32 v[36:37], v[36:37], v[46:47]
	v_pk_mul_f32 v[46:47], v[54:55], v[50:51]
	v_pk_mul_f32 v[2:3], v[34:35], v[2:3]
	v_pk_mul_f32 v[30:31], v[30:31], v[44:45]
	v_pk_mul_f32 v[6:7], v[36:37], v[6:7]
	v_pk_mul_f32 v[32:33], v[32:33], v[46:47]
	v_bfe_u32 v36, v2, 16, 1
	v_bfe_u32 v37, v3, 16, 1
	v_bfe_u32 v43, v30, 16, 1
	v_bfe_u32 v44, v31, 16, 1
	v_bfe_u32 v1, v33, 16, 1
	v_bfe_u32 v5, v32, 16, 1
	v_bfe_u32 v34, v7, 16, 1
	v_bfe_u32 v35, v6, 16, 1
	v_add3_u32 v31, v31, v44, s22
	v_add3_u32 v30, v30, v43, s22
	v_add3_u32 v3, v3, v37, s22
	v_add3_u32 v2, v2, v36, s22
	v_add3_u32 v6, v6, v35, s22
	v_add3_u32 v7, v7, v34, s22
	v_add3_u32 v5, v32, v5, s22
	v_add3_u32 v1, v33, v1, s22
	v_lshrrev_b32_e32 v2, 16, v2
	v_lshrrev_b32_e32 v3, 16, v3
	v_lshrrev_b32_e32 v30, 16, v30
	v_lshrrev_b32_e32 v31, 16, v31
	v_and_or_b32 v33, v1, s3, v31
	v_and_or_b32 v32, v5, s3, v30
	v_and_or_b32 v31, v7, s3, v3
	v_and_or_b32 v30, v6, s3, v2
	global_store_dwordx4 v[22:23], v[30:33], off offset:32
	s_nop 1
	v_mov_b32_e32 v30, v184
	v_mov_b32_e32 v31, v185
	v_mov_b32_e32 v32, v186
	v_mov_b32_e32 v33, v187
	s_nop 0
	v_mov_b32_e32 v34, v188
	v_mov_b32_e32 v35, v189
	v_mov_b32_e32 v36, v190
	v_mov_b32_e32 v37, v191
	v_and_b32_e32 v3, 0xffff0000, v9
	v_and_b32_e32 v2, 0xffff0000, v8
	v_lshlrev_b32_e32 v7, 16, v11
	v_lshlrev_b32_e32 v6, 16, v10
	v_and_b32_e32 v9, 0xffff0000, v11
	v_and_b32_e32 v8, 0xffff0000, v10
	v_mul_f32_e32 v10, 0xbfb8aa3b, v26
	v_mul_f32_e32 v11, 0xbfb8aa3b, v2
	v_mov_b32_e32 v5, v28
	v_mul_f32_e32 v28, 0xbfb8aa3b, v27
	v_mov_b32_e32 v1, v29
	v_mul_f32_e32 v29, 0xbfb8aa3b, v3
	v_mul_f32_e32 v43, 0xbfb8aa3b, v6
	v_mul_f32_e32 v45, 0xbfb8aa3b, v7
	v_exp_f32_e32 v10, v10
	v_exp_f32_e32 v11, v11
	v_exp_f32_e32 v28, v28
	v_exp_f32_e32 v29, v29
	v_mul_f32_e32 v44, 0xbfb8aa3b, v8
	v_mul_f32_e32 v46, 0xbfb8aa3b, v9
	v_exp_f32_e32 v43, v43
	v_exp_f32_e32 v45, v45
	v_exp_f32_e32 v44, v44
	v_exp_f32_e32 v46, v46
	v_add_f32_e32 v10, 1.0, v10
	v_add_f32_e32 v11, 1.0, v11
	v_add_f32_e32 v47, 1.0, v28
	v_add_f32_e32 v29, 1.0, v29
	v_add_f32_e32 v43, 1.0, v43
	v_add_f32_e32 v45, 1.0, v45
	v_rcp_f32_e32 v10, v10
	v_rcp_f32_e32 v28, v11
	v_rcp_f32_e32 v11, v47
	v_rcp_f32_e32 v29, v29
	v_add_f32_e32 v48, 1.0, v44
	v_add_f32_e32 v49, 1.0, v46
	v_rcp_f32_e32 v44, v43
	v_rcp_f32_e32 v45, v45
	v_rcp_f32_e32 v46, v48
	v_rcp_f32_e32 v47, v49
	v_pk_mul_f32 v[10:11], v[10:11], v[26:27]
	v_pk_mul_f32 v[2:3], v[28:29], v[2:3]
	v_pk_mul_f32 v[4:5], v[84:85], v[4:5] op_sel_hi:[0,1]
	v_pk_mul_f32 v[0:1], v[84:85], v[0:1] op_sel_hi:[0,1]
	v_pk_mul_f32 v[6:7], v[44:45], v[6:7]
	v_pk_mul_f32 v[8:9], v[46:47], v[8:9]
	v_mov_b32_e32 v26, v30
	v_mov_b32_e32 v27, v32
	v_mov_b32_e32 v32, v31
	v_mov_b32_e32 v28, v34
	v_mov_b32_e32 v29, v36
	v_mov_b32_e32 v36, v35
	v_pk_mul_f32 v[4:5], v[4:5], v[26:27]
	v_pk_mul_f32 v[0:1], v[0:1], v[32:33]
	v_pk_mul_f32 v[20:21], v[20:21], v[28:29]
	v_pk_mul_f32 v[24:25], v[24:25], v[36:37]
	v_pk_mul_f32 v[4:5], v[4:5], v[10:11]
	v_pk_mul_f32 v[0:1], v[0:1], v[2:3]
	v_pk_mul_f32 v[2:3], v[6:7], v[20:21]
	v_pk_mul_f32 v[6:7], v[8:9], v[24:25]
	v_bfe_u32 v20, v4, 16, 1
	v_bfe_u32 v21, v5, 16, 1
	v_bfe_u32 v24, v2, 16, 1
	v_bfe_u32 v25, v3, 16, 1
	v_bfe_u32 v8, v7, 16, 1
	v_bfe_u32 v9, v6, 16, 1
	v_bfe_u32 v10, v1, 16, 1
	v_bfe_u32 v11, v0, 16, 1
	v_add3_u32 v3, v3, v25, s22
	v_add3_u32 v2, v2, v24, s22
	v_add3_u32 v5, v5, v21, s22
	v_add3_u32 v4, v4, v20, s22
	v_add3_u32 v0, v0, v11, s22
	v_add3_u32 v1, v1, v10, s22
	v_add3_u32 v6, v6, v9, s22
	v_add3_u32 v7, v7, v8, s22
	v_lshrrev_b32_e32 v4, 16, v4
	v_lshrrev_b32_e32 v5, 16, v5
	v_lshrrev_b32_e32 v2, 16, v2
	v_lshrrev_b32_e32 v3, 16, v3
	v_and_or_b32 v3, v7, s3, v3
	v_and_or_b32 v2, v6, s3, v2
	v_and_or_b32 v1, v1, s3, v5
	v_and_or_b32 v0, v0, s3, v4
	global_store_dwordx4 v[22:23], v[0:3], off offset:48
	s_cbranch_scc1 .LBB0_1904
